# baseline (speedup 1.0000x reference)
.LBB0_841:
	s_lshl_b32 s10, s10, 5
	s_and_b32 s20, s10, 0x60
	s_mov_b64 s[10:11], 0x80
	s_add_i32 m0, s44, 0x18000
	v_lshl_add_u64 v[6:7], v[6:7], 0, s[10:11]
	s_lshl_b32 s18, s6, 13
	s_lshl_b32 s19, s20, 7
	s_waitcnt vmcnt(2)
	s_barrier
	global_load_lds_dwordx4 v[6:7], off
	v_lshl_add_u64 v[4:5], v[4:5], 0, s[10:11]
	s_add_i32 m0, s44, 0x1a000
	s_add_i32 s48, s44, 0x8000
	s_add_i32 s49, s44, 0xa000
	global_load_lds_dwordx4 v[4:5], off
	v_lshl_add_u64 v[0:1], v[0:1], 0, s[10:11]
	s_mov_b32 m0, s48
	s_add_u32 s12, s36, 0x40080
	global_load_lds_dwordx4 v[0:1], off
	v_lshl_add_u64 v[0:1], v[2:3], 0, s[10:11]
	s_mov_b32 m0, s49
	s_addc_u32 s13, s37, 0
	global_load_lds_dwordx4 v[0:1], off
	s_add_i32 m0, s44, 0x1c000
	v_lshl_add_u64 v[0:1], s[12:13], 0, v[128:129]
	global_load_lds_dwordx4 v[0:1], off
	v_lshl_add_u64 v[0:1], s[12:13], 0, v[130:131]
	s_add_i32 m0, s44, 0x1e000
	s_cmpk_lt_u32 s5, 0x100
	global_load_lds_dwordx4 v[0:1], off
	v_lshrrev_b32_e32 v0, 1, v9
	v_and_b32_e32 v0, 24, v0
	v_and_b32_e32 v1, 15, v9
	v_lshlrev_b32_e32 v2, 1, v0
	v_lshl_or_b32 v149, s6, 6, v1
	v_lshl_or_b32 v1, v1, 6, v2
	v_lshlrev_b32_e32 v2, 2, v9
	v_and_b32_e32 v2, 32, v2
	v_bitop3_b32 v3, v1, s18, v2 bitop3:0xde
	v_bitop3_b32 v153, v1, s19, v2 bitop3:0xde
	v_lshlrev_b32_e32 v1, 14, v13
	v_and_b32_e32 v1, 0xffff8000, v1
	v_lshl_add_u32 v1, v12, 11, v1
	v_and_b32_e32 v2, 1, v13
	v_lshl_or_b32 v1, v2, 6, v1
	v_lshl_add_u32 v138, v14, 1, v1
	v_lshlrev_b32_e32 v1, 14, v8
	v_and_b32_e32 v1, 0xffff8000, v1
	s_waitcnt vmcnt(6)
	v_lshl_add_u32 v1, v10, 11, v1
	v_and_b32_e32 v2, 1, v8
	s_cselect_b64 s[18:19], -1, 0
	v_mov_b32_e32 v137, 0
	v_lshl_or_b32 v1, v2, 6, v1
	s_add_i32 s52, 0, 0x10000
	s_add_i32 s53, 0, 0x14000
	s_sext_i32_i16 s29, s4
	s_ashr_i32 s50, s58, 31
	s_mov_b32 s51, s58
	v_mov_b32_e32 v139, v137
	v_lshl_add_u32 v140, v11, 1, v1
	v_mov_b32_e32 v141, v137
	v_mov_b64_e32 v[142:143], 0x580
	v_mov_b64_e32 v[144:145], 0x57f
	v_add_u32_e32 v157, s52, v153
	v_add_u32_e32 v161, s53, v153
	v_add_u32_e32 v162, 0, v3
	s_movk_i32 s70, 0x1600
	s_lshl_b32 s6, s20, 1
	v_lshlrev_b32_e32 v136, 1, v0
	s_mov_b32 s71, s7
	s_barrier
	v_lshl_add_u32 v232, s28, 8, v149
	v_lshlrev_b32_e32 v232, 2, v232
	global_load_dword v233, v232, s[66:67]
	global_load_dword v234, v232, s[66:67] offset:64
	global_load_dword v235, v232, s[66:67] offset:128
	global_load_dword v236, v232, s[66:67] offset:192
	global_load_dword v237, v232, s[66:67] offset:512
	global_load_dword v238, v232, s[66:67] offset:576
	global_load_dword v239, v232, s[66:67] offset:640
	global_load_dword v240, v232, s[66:67] offset:704
	s_branch .LBB0_844

.LBB0_850:
	v_lshl_add_u32 v164, s28, 8, v149
	v_ashrrev_i32_e32 v165, 31, v164
	v_lshl_add_u64 v[146:147], v[164:165], 2, s[66:67]
	v_mov_b32_e32 v166, v233
	v_or_b32_e32 v176, 16, v164
	v_ashrrev_i32_e32 v177, 31, v176
	v_mov_b32_e32 v174, v118
	v_mov_b32_e32 v175, v114
	v_mov_b32_e32 v114, v119
	v_lshl_add_u64 v[118:119], v[176:177], 2, s[66:67]
	v_mov_b32_e32 v180, v234
	v_or_b32_e32 v158, 32, v164
	v_add_u32_e32 v150, 0x80, v164
	v_mov_b32_e32 v168, v124
	v_mov_b32_e32 v169, v120
	v_mov_b32_e32 v172, v116
	v_or_b32_e32 v154, 48, v164
	v_add_u32_e32 v146, 0x90, v164
	v_add_u32_e32 v124, 0xa0, v164
	v_add_u32_e32 v116, 0xb0, v164
	v_ashrrev_i32_e32 v159, 31, v158
	v_ashrrev_i32_e32 v151, 31, v150
	v_mov_b32_e32 v120, v125
	v_mov_b32_e32 v170, v126
	v_mov_b32_e32 v171, v122
	v_mov_b32_e32 v122, v127
	v_mov_b32_e32 v173, v112
	v_mov_b32_e32 v112, v117
	v_ashrrev_i32_e32 v155, 31, v154
	v_ashrrev_i32_e32 v147, 31, v146
	v_ashrrev_i32_e32 v125, 31, v124
	v_ashrrev_i32_e32 v117, 31, v116
	v_lshl_add_u64 v[126:127], v[158:159], 2, s[66:67]
	v_lshl_add_u64 v[118:119], v[150:151], 2, s[66:67]
	v_lshl_add_u64 v[178:179], v[154:155], 2, s[66:67]
	v_lshl_add_u64 v[182:183], v[146:147], 2, s[66:67]
	v_lshl_add_u64 v[184:185], v[124:125], 2, s[66:67]
	v_lshl_add_u64 v[188:189], v[116:117], 2, s[66:67]
	v_mov_b32_e32 v160, v235
	v_mov_b32_e32 v156, v236
	v_mov_b32_e32 v152, v237
	v_mov_b32_e32 v148, v238
	s_nop 0
	v_mov_b32_e32 v126, v239
	v_mov_b32_e32 v118, v240
	s_cmp_lg_u64 s[4:5], 0
	s_cselect_b32 s92, s22, s28
	v_lshl_add_u32 v232, s92, 8, v149
	v_lshlrev_b32_e32 v232, 2, v232
	global_load_dword v233, v232, s[66:67]
	global_load_dword v234, v232, s[66:67] offset:64
	global_load_dword v235, v232, s[66:67] offset:128
	global_load_dword v236, v232, s[66:67] offset:192
	global_load_dword v237, v232, s[66:67] offset:512
	global_load_dword v238, v232, s[66:67] offset:576
	global_load_dword v239, v232, s[66:67] offset:640
	global_load_dword v240, v232, s[66:67] offset:704
	v_mov_b32_e32 v165, v108
	v_mov_b32_e32 v108, v105
	s_lshl_b32 s28, s29, 7
	s_ashr_i32 s29, s28, 31
	s_lshl_b64 s[28:29], s[28:29], 1
	s_andn2_b64 vcc, exec, s[4:5]
	s_mov_b64 s[4:5], -1
	v_pk_mul_f32 v[168:169], v[168:169], v[166:167] op_sel_hi:[1,0]
	v_pk_mul_f32 v[120:121], v[120:121], v[166:167] op_sel_hi:[1,0]
	v_mul_f32_e32 v117, 0xbfb8aa3b, v169
	v_mul_f32_e32 v119, 0xbfb8aa3b, v121
	v_exp_f32_e32 v117, v117
	v_exp_f32_e32 v119, v119
	v_pk_mul_f32 v[112:113], v[112:113], v[166:167] op_sel_hi:[1,0]
	v_pk_mul_f32 v[170:171], v[170:171], v[166:167] op_sel_hi:[1,0]
	v_pk_mul_f32 v[122:123], v[122:123], v[166:167] op_sel_hi:[1,0]
	v_pk_mul_f32 v[172:173], v[172:173], v[166:167] op_sel_hi:[1,0]
	v_pk_mul_f32 v[174:175], v[174:175], v[166:167] op_sel_hi:[1,0]
	v_mul_f32_e32 v151, 0xbfb8aa3b, v113
	v_add_f32_e32 v117, 1.0, v117
	v_pk_mul_f32 v[114:115], v[114:115], v[166:167] op_sel_hi:[1,0]
	v_mul_f32_e32 v125, 0xbfb8aa3b, v171
	v_mul_f32_e32 v127, 0xbfb8aa3b, v123
	v_mul_f32_e32 v147, 0xbfb8aa3b, v173
	v_mul_f32_e32 v155, 0xbfb8aa3b, v175
	v_exp_f32_e32 v151, v151
	v_add_f32_e32 v119, 1.0, v119
	v_rcp_f32_e32 v117, v117
	v_mul_f32_e32 v159, 0xbfb8aa3b, v115
	v_exp_f32_e32 v125, v125
	v_exp_f32_e32 v127, v127
	v_exp_f32_e32 v147, v147
	v_exp_f32_e32 v155, v155
	v_rcp_f32_e32 v119, v119
	v_exp_f32_e32 v159, v159
	v_add_f32_e32 v151, 1.0, v151
	v_mul_f32_e32 v117, v169, v117
	v_add_f32_e32 v125, 1.0, v125
	v_add_f32_e32 v127, 1.0, v127
	v_add_f32_e32 v147, 1.0, v147
	v_add_f32_e32 v155, 1.0, v155
	v_rcp_f32_e32 v151, v151
	v_mul_f32_e32 v119, v121, v119
	v_mul_f32_e32 v117, v168, v117
	v_rcp_f32_e32 v125, v125
	v_rcp_f32_e32 v127, v127
	v_rcp_f32_e32 v147, v147
	v_rcp_f32_e32 v155, v155
	v_mul_f32_e32 v119, v120, v119
	v_cvt_pk_bf16_f32 v120, v117, v119
	v_add_f32_e32 v117, 1.0, v159
	v_rcp_f32_e32 v117, v117
	v_mul_f32_e32 v113, v113, v151
	v_mul_f32_e32 v121, v171, v125
	v_mul_f32_e32 v123, v123, v127
	v_mul_f32_e32 v125, v173, v147
	v_mul_f32_e32 v112, v112, v113
	v_mul_f32_e32 v113, v175, v155
	v_mul_f32_e32 v121, v170, v121
	v_mul_f32_e32 v122, v122, v123
	v_mul_f32_e32 v123, v172, v125
	v_mul_f32_e32 v113, v174, v113
	v_mul_f32_e32 v115, v115, v117
	v_cvt_pk_bf16_f32 v121, v121, v122
	v_mul_f32_e32 v114, v114, v115
	v_cvt_pk_bf16_f32 v122, v123, v112
	v_cvt_pk_bf16_f32 v123, v113, v114
	v_mov_b64_e32 v[112:113], s[64:65]
	v_mad_i64_i32 v[114:115], s[12:13], v164, s70, v[112:113]
	v_mov_b32_e32 v164, v104
	v_pk_mul_f32 v[164:165], v[164:165], v[180:181] op_sel_hi:[1,0]
	v_lshl_add_u64 v[114:115], v[114:115], 0, s[28:29]
	v_mul_f32_e32 v104, 0xbfb8aa3b, v165
	v_exp_f32_e32 v117, v104
	v_pk_mul_f32 v[104:105], v[108:109], v[180:181] op_sel_hi:[1,0]
	v_lshl_add_u64 v[114:115], v[114:115], 0, s[6:7]
	v_mul_f32_e32 v108, 0xbfb8aa3b, v105
	v_exp_f32_e32 v108, v108
	v_lshl_add_u64 v[114:115], v[114:115], 0, v[136:137]
	v_add_f32_e32 v109, 1.0, v117
	global_store_dwordx4 v[114:115], v[120:123], off
	v_add_f32_e32 v108, 1.0, v108
	v_rcp_f32_e32 v114, v109
	v_rcp_f32_e32 v115, v108
	v_mov_b32_e32 v108, v106
	v_mov_b32_e32 v109, v110
	v_pk_mul_f32 v[108:109], v[108:109], v[180:181] op_sel_hi:[1,0]
	v_mul_f32_e32 v110, v165, v114
	v_mul_f32_e32 v106, 0xbfb8aa3b, v109
	v_exp_f32_e32 v106, v106
	v_mul_f32_e32 v114, v164, v110
	v_mov_b32_e32 v110, v107
	v_mul_f32_e32 v105, v105, v115
	v_add_f32_e32 v106, 1.0, v106
	v_rcp_f32_e32 v115, v106
	v_pk_mul_f32 v[106:107], v[110:111], v[180:181] op_sel_hi:[1,0]
	v_mul_f32_e32 v111, v104, v105
	v_mul_f32_e32 v110, 0xbfb8aa3b, v107
	v_exp_f32_e32 v110, v110
	v_mul_f32_e32 v104, v109, v115
	v_mul_f32_e32 v108, v108, v104
	v_mov_b32_e32 v105, v100
	v_add_f32_e32 v104, 1.0, v110
	v_rcp_f32_e32 v109, v104
	v_mov_b32_e32 v104, v96
	v_pk_mul_f32 v[104:105], v[104:105], v[180:181] op_sel_hi:[1,0]
	s_nop 0
	v_mul_f32_e32 v96, 0xbfb8aa3b, v105
	v_exp_f32_e32 v100, v96
	v_mul_f32_e32 v96, v107, v109
	v_mul_f32_e32 v106, v106, v96
	v_cvt_pk_bf16_f32 v96, v114, v111
	v_add_f32_e32 v100, 1.0, v100
	v_rcp_f32_e32 v107, v100
	v_mov_b32_e32 v100, v97
	v_pk_mul_f32 v[100:101], v[100:101], v[180:181] op_sel_hi:[1,0]
	v_mul_f32_e32 v105, v105, v107
	v_mul_f32_e32 v97, 0xbfb8aa3b, v101
	v_exp_f32_e32 v109, v97
	v_cvt_pk_bf16_f32 v97, v108, v106
	v_mul_f32_e32 v106, v104, v105
	v_mov_b32_e32 v105, v102
	v_add_f32_e32 v104, 1.0, v109
	v_rcp_f32_e32 v107, v104
	v_mov_b32_e32 v104, v98
	v_pk_mul_f32 v[104:105], v[104:105], v[180:181] op_sel_hi:[1,0]
	v_mov_b32_e32 v102, v99
	v_mul_f32_e32 v98, 0xbfb8aa3b, v105
	v_exp_f32_e32 v108, v98
	v_pk_mul_f32 v[98:99], v[102:103], v[180:181] op_sel_hi:[1,0]
	v_mul_f32_e32 v101, v101, v107
	v_mul_f32_e32 v102, 0xbfb8aa3b, v99
	v_exp_f32_e32 v102, v102
	v_add_f32_e32 v103, 1.0, v108
	v_rcp_f32_e32 v103, v103
	v_mul_f32_e32 v100, v100, v101
	v_add_f32_e32 v102, 1.0, v102
	v_rcp_f32_e32 v102, v102
	v_mul_f32_e32 v101, v105, v103
	v_mov_b32_e32 v103, v92
	v_mov_b32_e32 v92, v89
	v_mul_f32_e32 v99, v99, v102
	v_mov_b32_e32 v102, v88
	v_pk_mul_f32 v[102:103], v[102:103], v[160:161] op_sel_hi:[1,0]
	v_mul_f32_e32 v101, v104, v101
	v_mul_f32_e32 v88, 0xbfb8aa3b, v103
	v_exp_f32_e32 v104, v88
	v_pk_mul_f32 v[88:89], v[92:93], v[160:161] op_sel_hi:[1,0]
	v_mul_f32_e32 v99, v98, v99
	v_mul_f32_e32 v92, 0xbfb8aa3b, v89
	v_exp_f32_e32 v92, v92
	v_cvt_pk_bf16_f32 v98, v106, v100
	v_cvt_pk_bf16_f32 v99, v101, v99
	v_mad_i64_i32 v[100:101], s[12:13], v176, s70, v[112:113]
	v_lshl_add_u64 v[100:101], v[100:101], 0, s[28:29]
	v_lshl_add_u64 v[100:101], v[100:101], 0, s[6:7]
	v_lshl_add_u64 v[100:101], v[100:101], 0, v[136:137]
	v_add_f32_e32 v93, 1.0, v104
	v_add_f32_e32 v92, 1.0, v92
	global_store_dwordx4 v[100:101], v[96:99], off
	s_nop 1
	v_rcp_f32_e32 v96, v93
	v_rcp_f32_e32 v97, v92
	v_mov_b32_e32 v92, v90
	v_mov_b32_e32 v93, v94
	v_pk_mul_f32 v[92:93], v[92:93], v[160:161] op_sel_hi:[1,0]
	v_mul_f32_e32 v94, v103, v96
	v_mul_f32_e32 v90, 0xbfb8aa3b, v93
	v_exp_f32_e32 v90, v90
	v_mul_f32_e32 v96, v102, v94
	v_mov_b32_e32 v94, v91
	v_mul_f32_e32 v89, v89, v97
	v_add_f32_e32 v90, 1.0, v90
	v_rcp_f32_e32 v97, v90
	v_pk_mul_f32 v[90:91], v[94:95], v[160:161] op_sel_hi:[1,0]
	v_mul_f32_e32 v95, v88, v89
	v_mul_f32_e32 v94, 0xbfb8aa3b, v91
	v_exp_f32_e32 v94, v94
	v_mul_f32_e32 v88, v93, v97
	v_mul_f32_e32 v92, v92, v88
	v_mov_b32_e32 v89, v84
	v_add_f32_e32 v88, 1.0, v94
	v_rcp_f32_e32 v93, v88
	v_mov_b32_e32 v88, v80
	v_pk_mul_f32 v[88:89], v[88:89], v[160:161] op_sel_hi:[1,0]
	s_nop 0
	v_mul_f32_e32 v80, 0xbfb8aa3b, v89
	v_exp_f32_e32 v84, v80
	v_mul_f32_e32 v80, v91, v93
	v_mul_f32_e32 v90, v90, v80
	v_cvt_pk_bf16_f32 v80, v96, v95
	v_add_f32_e32 v84, 1.0, v84
	v_rcp_f32_e32 v91, v84
	v_mov_b32_e32 v84, v81
	v_pk_mul_f32 v[84:85], v[84:85], v[160:161] op_sel_hi:[1,0]
	v_mul_f32_e32 v89, v89, v91
	v_mul_f32_e32 v81, 0xbfb8aa3b, v85
	v_exp_f32_e32 v93, v81
	v_cvt_pk_bf16_f32 v81, v92, v90
	v_mul_f32_e32 v90, v88, v89
	v_mov_b32_e32 v89, v86
	v_add_f32_e32 v88, 1.0, v93
	v_rcp_f32_e32 v91, v88
	v_mov_b32_e32 v88, v82
	v_pk_mul_f32 v[88:89], v[88:89], v[160:161] op_sel_hi:[1,0]
	v_mov_b32_e32 v86, v83
	v_mul_f32_e32 v82, 0xbfb8aa3b, v89
	v_exp_f32_e32 v92, v82
	v_pk_mul_f32 v[82:83], v[86:87], v[160:161] op_sel_hi:[1,0]
	v_mul_f32_e32 v85, v85, v91
	v_mul_f32_e32 v86, 0xbfb8aa3b, v83
	v_exp_f32_e32 v86, v86
	v_add_f32_e32 v87, 1.0, v92
	v_rcp_f32_e32 v87, v87
	v_mul_f32_e32 v84, v84, v85
	v_add_f32_e32 v86, 1.0, v86
	v_rcp_f32_e32 v86, v86
	v_mul_f32_e32 v85, v89, v87
	v_mov_b32_e32 v87, v76
	v_mov_b32_e32 v76, v73
	v_mul_f32_e32 v83, v83, v86
	v_mov_b32_e32 v86, v72
	v_pk_mul_f32 v[86:87], v[86:87], v[156:157] op_sel_hi:[1,0]
	v_mul_f32_e32 v85, v88, v85
	v_mul_f32_e32 v72, 0xbfb8aa3b, v87
	v_exp_f32_e32 v88, v72
	v_pk_mul_f32 v[72:73], v[76:77], v[156:157] op_sel_hi:[1,0]
	v_mul_f32_e32 v83, v82, v83
	v_mul_f32_e32 v76, 0xbfb8aa3b, v73
	v_exp_f32_e32 v76, v76
	v_cvt_pk_bf16_f32 v82, v90, v84
	v_cvt_pk_bf16_f32 v83, v85, v83
	v_mad_i64_i32 v[84:85], s[12:13], v158, s70, v[112:113]
	v_lshl_add_u64 v[84:85], v[84:85], 0, s[28:29]
	v_lshl_add_u64 v[84:85], v[84:85], 0, s[6:7]
	v_lshl_add_u64 v[84:85], v[84:85], 0, v[136:137]
	v_add_f32_e32 v77, 1.0, v88
	v_add_f32_e32 v76, 1.0, v76
	global_store_dwordx4 v[84:85], v[80:83], off
	s_nop 1
	v_rcp_f32_e32 v80, v77
	v_rcp_f32_e32 v81, v76
	v_mov_b32_e32 v76, v74
	v_mov_b32_e32 v77, v78
	v_pk_mul_f32 v[76:77], v[76:77], v[156:157] op_sel_hi:[1,0]
	v_mul_f32_e32 v78, v87, v80
	v_mul_f32_e32 v74, 0xbfb8aa3b, v77
	v_exp_f32_e32 v74, v74
	v_mul_f32_e32 v80, v86, v78
	v_mov_b32_e32 v78, v75
	v_mul_f32_e32 v73, v73, v81
	v_add_f32_e32 v74, 1.0, v74
	v_rcp_f32_e32 v81, v74
	v_pk_mul_f32 v[74:75], v[78:79], v[156:157] op_sel_hi:[1,0]
	v_mul_f32_e32 v79, v72, v73
	v_mul_f32_e32 v78, 0xbfb8aa3b, v75
	v_exp_f32_e32 v78, v78
	v_mul_f32_e32 v72, v77, v81
	v_mul_f32_e32 v76, v76, v72
	v_mov_b32_e32 v73, v68
	v_add_f32_e32 v72, 1.0, v78
	v_rcp_f32_e32 v77, v72
	v_mov_b32_e32 v72, v64
	v_pk_mul_f32 v[72:73], v[72:73], v[156:157] op_sel_hi:[1,0]
	s_nop 0
	v_mul_f32_e32 v64, 0xbfb8aa3b, v73
	v_exp_f32_e32 v68, v64
	v_mul_f32_e32 v64, v75, v77
	v_mul_f32_e32 v74, v74, v64
	v_cvt_pk_bf16_f32 v64, v80, v79
	v_add_f32_e32 v68, 1.0, v68
	v_rcp_f32_e32 v75, v68
	v_mov_b32_e32 v68, v65
	v_pk_mul_f32 v[68:69], v[68:69], v[156:157] op_sel_hi:[1,0]
	v_mul_f32_e32 v73, v73, v75
	v_mul_f32_e32 v65, 0xbfb8aa3b, v69
	v_exp_f32_e32 v77, v65
	v_cvt_pk_bf16_f32 v65, v76, v74
	v_mul_f32_e32 v74, v72, v73
	v_mov_b32_e32 v73, v70
	v_add_f32_e32 v72, 1.0, v77
	v_rcp_f32_e32 v75, v72
	v_mov_b32_e32 v72, v66
	v_pk_mul_f32 v[72:73], v[72:73], v[156:157] op_sel_hi:[1,0]
	v_mov_b32_e32 v70, v67
	v_mul_f32_e32 v66, 0xbfb8aa3b, v73
	v_exp_f32_e32 v76, v66
	v_pk_mul_f32 v[66:67], v[70:71], v[156:157] op_sel_hi:[1,0]
	v_mul_f32_e32 v69, v69, v75
	v_mul_f32_e32 v70, 0xbfb8aa3b, v67
	v_exp_f32_e32 v70, v70
	v_add_f32_e32 v71, 1.0, v76
	v_rcp_f32_e32 v71, v71
	v_mul_f32_e32 v68, v68, v69
	v_add_f32_e32 v70, 1.0, v70
	v_rcp_f32_e32 v70, v70
	v_mul_f32_e32 v69, v73, v71
	v_mov_b32_e32 v71, v60
	v_mov_b32_e32 v60, v57
	v_mul_f32_e32 v67, v67, v70
	v_mov_b32_e32 v70, v56
	v_pk_mul_f32 v[70:71], v[70:71], v[152:153] op_sel_hi:[1,0]
	v_mul_f32_e32 v69, v72, v69
	v_mul_f32_e32 v56, 0xbfb8aa3b, v71
	v_exp_f32_e32 v72, v56
	v_pk_mul_f32 v[56:57], v[60:61], v[152:153] op_sel_hi:[1,0]
	v_mul_f32_e32 v67, v66, v67
	v_mul_f32_e32 v60, 0xbfb8aa3b, v57
	v_exp_f32_e32 v60, v60
	v_cvt_pk_bf16_f32 v66, v74, v68
	v_cvt_pk_bf16_f32 v67, v69, v67
	v_mad_i64_i32 v[68:69], s[12:13], v154, s70, v[112:113]
	v_lshl_add_u64 v[68:69], v[68:69], 0, s[28:29]
	v_lshl_add_u64 v[68:69], v[68:69], 0, s[6:7]
	v_lshl_add_u64 v[68:69], v[68:69], 0, v[136:137]
	v_add_f32_e32 v61, 1.0, v72
	v_add_f32_e32 v60, 1.0, v60
	global_store_dwordx4 v[68:69], v[64:67], off
	s_nop 1
	v_rcp_f32_e32 v64, v61
	v_rcp_f32_e32 v65, v60
	v_mov_b32_e32 v60, v58
	v_mov_b32_e32 v61, v62
	v_pk_mul_f32 v[60:61], v[60:61], v[152:153] op_sel_hi:[1,0]
	v_mul_f32_e32 v62, v71, v64
	v_mul_f32_e32 v58, 0xbfb8aa3b, v61
	v_exp_f32_e32 v58, v58
	v_mul_f32_e32 v64, v70, v62
	v_mov_b32_e32 v62, v59
	v_mul_f32_e32 v57, v57, v65
	v_add_f32_e32 v58, 1.0, v58
	v_rcp_f32_e32 v65, v58
	v_pk_mul_f32 v[58:59], v[62:63], v[152:153] op_sel_hi:[1,0]
	v_mul_f32_e32 v63, v56, v57
	v_mul_f32_e32 v62, 0xbfb8aa3b, v59
	v_exp_f32_e32 v62, v62
	v_mul_f32_e32 v56, v61, v65
	v_mul_f32_e32 v60, v60, v56
	v_mov_b32_e32 v57, v52
	v_add_f32_e32 v56, 1.0, v62
	v_rcp_f32_e32 v61, v56
	v_mov_b32_e32 v56, v48
	v_pk_mul_f32 v[56:57], v[56:57], v[152:153] op_sel_hi:[1,0]
	s_nop 0
	v_mul_f32_e32 v48, 0xbfb8aa3b, v57
	v_exp_f32_e32 v52, v48
	v_mul_f32_e32 v48, v59, v61
	v_mul_f32_e32 v58, v58, v48
	v_cvt_pk_bf16_f32 v48, v64, v63
	v_add_f32_e32 v52, 1.0, v52
	v_rcp_f32_e32 v59, v52
	v_mov_b32_e32 v52, v49
	v_pk_mul_f32 v[52:53], v[52:53], v[152:153] op_sel_hi:[1,0]
	v_mul_f32_e32 v57, v57, v59
	v_mul_f32_e32 v49, 0xbfb8aa3b, v53
	v_exp_f32_e32 v61, v49
	v_cvt_pk_bf16_f32 v49, v60, v58
	v_mul_f32_e32 v58, v56, v57
	v_mov_b32_e32 v57, v54
	v_add_f32_e32 v56, 1.0, v61
	v_rcp_f32_e32 v59, v56
	v_mov_b32_e32 v56, v50
	v_pk_mul_f32 v[56:57], v[56:57], v[152:153] op_sel_hi:[1,0]
	v_mov_b32_e32 v54, v51
	v_mul_f32_e32 v50, 0xbfb8aa3b, v57
	v_exp_f32_e32 v60, v50
	v_pk_mul_f32 v[50:51], v[54:55], v[152:153] op_sel_hi:[1,0]
	v_mul_f32_e32 v53, v53, v59
	v_mul_f32_e32 v54, 0xbfb8aa3b, v51
	v_exp_f32_e32 v54, v54
	v_add_f32_e32 v55, 1.0, v60
	v_rcp_f32_e32 v55, v55
	v_mul_f32_e32 v52, v52, v53
	v_add_f32_e32 v54, 1.0, v54
	v_rcp_f32_e32 v54, v54
	v_mul_f32_e32 v53, v57, v55
	v_mov_b32_e32 v55, v44
	v_mov_b32_e32 v44, v41
	v_mul_f32_e32 v51, v51, v54
	v_mov_b32_e32 v54, v40
	v_pk_mul_f32 v[54:55], v[54:55], v[148:149] op_sel_hi:[1,0]
	v_mul_f32_e32 v53, v56, v53
	v_mul_f32_e32 v40, 0xbfb8aa3b, v55
	v_exp_f32_e32 v56, v40
	v_pk_mul_f32 v[40:41], v[44:45], v[148:149] op_sel_hi:[1,0]
	v_mul_f32_e32 v51, v50, v51
	v_mul_f32_e32 v44, 0xbfb8aa3b, v41
	v_exp_f32_e32 v44, v44
	v_cvt_pk_bf16_f32 v50, v58, v52
	v_cvt_pk_bf16_f32 v51, v53, v51
	v_mad_i64_i32 v[52:53], s[12:13], v150, s70, v[112:113]
	v_lshl_add_u64 v[52:53], v[52:53], 0, s[28:29]
	v_lshl_add_u64 v[52:53], v[52:53], 0, s[6:7]
	v_lshl_add_u64 v[52:53], v[52:53], 0, v[136:137]
	v_add_f32_e32 v45, 1.0, v56
	v_add_f32_e32 v44, 1.0, v44
	global_store_dwordx4 v[52:53], v[48:51], off
	s_nop 1
	v_rcp_f32_e32 v48, v45
	v_rcp_f32_e32 v49, v44
	v_mov_b32_e32 v44, v42
	v_mov_b32_e32 v45, v46
	v_pk_mul_f32 v[44:45], v[44:45], v[148:149] op_sel_hi:[1,0]
	v_mul_f32_e32 v46, v55, v48
	v_mul_f32_e32 v42, 0xbfb8aa3b, v45
	v_exp_f32_e32 v42, v42
	v_mul_f32_e32 v48, v54, v46
	v_mov_b32_e32 v46, v43
	v_mul_f32_e32 v41, v41, v49
	v_add_f32_e32 v42, 1.0, v42
	v_rcp_f32_e32 v49, v42
	v_pk_mul_f32 v[42:43], v[46:47], v[148:149] op_sel_hi:[1,0]
	v_mul_f32_e32 v47, v40, v41
	v_mul_f32_e32 v46, 0xbfb8aa3b, v43
	v_exp_f32_e32 v46, v46
	v_mul_f32_e32 v40, v45, v49
	v_mul_f32_e32 v44, v44, v40
	v_mov_b32_e32 v41, v36
	v_add_f32_e32 v40, 1.0, v46
	v_rcp_f32_e32 v45, v40
	v_mov_b32_e32 v40, v32
	v_pk_mul_f32 v[40:41], v[40:41], v[148:149] op_sel_hi:[1,0]
	s_nop 0
	v_mul_f32_e32 v32, 0xbfb8aa3b, v41
	v_exp_f32_e32 v36, v32
	v_mul_f32_e32 v32, v43, v45
	v_mul_f32_e32 v42, v42, v32
	v_cvt_pk_bf16_f32 v32, v48, v47
	v_add_f32_e32 v36, 1.0, v36
	v_rcp_f32_e32 v43, v36
	v_mov_b32_e32 v36, v33
	v_pk_mul_f32 v[36:37], v[36:37], v[148:149] op_sel_hi:[1,0]
	v_mul_f32_e32 v41, v41, v43
	v_mul_f32_e32 v33, 0xbfb8aa3b, v37
	v_exp_f32_e32 v45, v33
	v_cvt_pk_bf16_f32 v33, v44, v42
	v_mul_f32_e32 v42, v40, v41
	v_mov_b32_e32 v41, v38
	v_add_f32_e32 v40, 1.0, v45
	v_rcp_f32_e32 v43, v40
	v_mov_b32_e32 v40, v34
	v_pk_mul_f32 v[40:41], v[40:41], v[148:149] op_sel_hi:[1,0]
	v_mov_b32_e32 v38, v35
	v_mul_f32_e32 v34, 0xbfb8aa3b, v41
	v_exp_f32_e32 v44, v34
	v_pk_mul_f32 v[34:35], v[38:39], v[148:149] op_sel_hi:[1,0]
	v_mul_f32_e32 v37, v37, v43
	v_mul_f32_e32 v38, 0xbfb8aa3b, v35
	v_exp_f32_e32 v38, v38
	v_add_f32_e32 v39, 1.0, v44
	v_rcp_f32_e32 v39, v39
	v_mul_f32_e32 v36, v36, v37
	v_add_f32_e32 v38, 1.0, v38
	v_rcp_f32_e32 v38, v38
	v_mul_f32_e32 v37, v41, v39
	v_mov_b32_e32 v39, v28
	v_mov_b32_e32 v28, v25
	v_mul_f32_e32 v35, v35, v38
	v_mov_b32_e32 v38, v24
	v_pk_mul_f32 v[38:39], v[38:39], v[126:127] op_sel_hi:[1,0]
	v_mul_f32_e32 v37, v40, v37
	v_mul_f32_e32 v24, 0xbfb8aa3b, v39
	v_exp_f32_e32 v40, v24
	v_pk_mul_f32 v[24:25], v[28:29], v[126:127] op_sel_hi:[1,0]
	v_mul_f32_e32 v35, v34, v35
	v_mul_f32_e32 v28, 0xbfb8aa3b, v25
	v_exp_f32_e32 v28, v28
	v_cvt_pk_bf16_f32 v34, v42, v36
	v_cvt_pk_bf16_f32 v35, v37, v35
	v_mad_i64_i32 v[36:37], s[12:13], v146, s70, v[112:113]
	v_lshl_add_u64 v[36:37], v[36:37], 0, s[28:29]
	v_lshl_add_u64 v[36:37], v[36:37], 0, s[6:7]
	v_lshl_add_u64 v[36:37], v[36:37], 0, v[136:137]
	v_add_f32_e32 v29, 1.0, v40
	v_add_f32_e32 v28, 1.0, v28
	global_store_dwordx4 v[36:37], v[32:35], off
	s_nop 1
	v_rcp_f32_e32 v32, v29
	v_rcp_f32_e32 v33, v28
	v_mov_b32_e32 v28, v26
	v_mov_b32_e32 v29, v30
	v_pk_mul_f32 v[28:29], v[28:29], v[126:127] op_sel_hi:[1,0]
	v_mul_f32_e32 v30, v39, v32
	v_mul_f32_e32 v26, 0xbfb8aa3b, v29
	v_exp_f32_e32 v26, v26
	v_mul_f32_e32 v32, v38, v30
	v_mov_b32_e32 v30, v27
	v_mul_f32_e32 v25, v25, v33
	v_add_f32_e32 v26, 1.0, v26
	v_rcp_f32_e32 v33, v26
	v_pk_mul_f32 v[26:27], v[30:31], v[126:127] op_sel_hi:[1,0]
	v_mul_f32_e32 v31, v24, v25
	v_mul_f32_e32 v30, 0xbfb8aa3b, v27
	v_exp_f32_e32 v30, v30
	v_mul_f32_e32 v24, v29, v33
	v_mul_f32_e32 v28, v28, v24
	v_mov_b32_e32 v25, v20
	v_add_f32_e32 v24, 1.0, v30
	v_rcp_f32_e32 v29, v24
	v_mov_b32_e32 v24, v16
	v_pk_mul_f32 v[24:25], v[24:25], v[126:127] op_sel_hi:[1,0]
	s_nop 0
	v_mul_f32_e32 v16, 0xbfb8aa3b, v25
	v_exp_f32_e32 v20, v16
	v_mul_f32_e32 v16, v27, v29
	v_mul_f32_e32 v26, v26, v16
	v_cvt_pk_bf16_f32 v16, v32, v31
	v_add_f32_e32 v20, 1.0, v20
	v_rcp_f32_e32 v27, v20
	v_mov_b32_e32 v20, v17
	v_pk_mul_f32 v[20:21], v[20:21], v[126:127] op_sel_hi:[1,0]
	v_mul_f32_e32 v25, v25, v27
	v_mul_f32_e32 v17, 0xbfb8aa3b, v21
	v_exp_f32_e32 v29, v17
	v_cvt_pk_bf16_f32 v17, v28, v26
	v_mul_f32_e32 v26, v24, v25
	v_mov_b32_e32 v25, v22
	v_add_f32_e32 v24, 1.0, v29
	v_rcp_f32_e32 v27, v24
	v_mov_b32_e32 v24, v18
	v_pk_mul_f32 v[24:25], v[24:25], v[126:127] op_sel_hi:[1,0]
	v_mov_b32_e32 v22, v19
	v_mul_f32_e32 v18, 0xbfb8aa3b, v25
	v_exp_f32_e32 v28, v18
	v_pk_mul_f32 v[18:19], v[22:23], v[126:127] op_sel_hi:[1,0]
	v_mul_f32_e32 v21, v21, v27
	v_mul_f32_e32 v22, 0xbfb8aa3b, v19
	v_exp_f32_e32 v22, v22
	v_add_f32_e32 v23, 1.0, v28
	v_rcp_f32_e32 v23, v23
	v_mul_f32_e32 v20, v20, v21
	v_add_f32_e32 v22, 1.0, v22
	v_rcp_f32_e32 v22, v22
	v_mul_f32_e32 v21, v25, v23
	v_mov_b32_e32 v23, v12
	v_mov_b32_e32 v12, v9
	v_mul_f32_e32 v19, v19, v22
	v_mov_b32_e32 v22, v8
	v_pk_mul_f32 v[22:23], v[22:23], v[118:119] op_sel_hi:[1,0]
	v_mul_f32_e32 v21, v24, v21
	v_mul_f32_e32 v8, 0xbfb8aa3b, v23
	v_exp_f32_e32 v24, v8
	v_pk_mul_f32 v[8:9], v[12:13], v[118:119] op_sel_hi:[1,0]
	v_mul_f32_e32 v19, v18, v19
	v_mul_f32_e32 v12, 0xbfb8aa3b, v9
	v_exp_f32_e32 v12, v12
	v_cvt_pk_bf16_f32 v18, v26, v20
	v_cvt_pk_bf16_f32 v19, v21, v19
	v_mad_i64_i32 v[20:21], s[12:13], v124, s70, v[112:113]
	v_lshl_add_u64 v[20:21], v[20:21], 0, s[28:29]
	v_lshl_add_u64 v[20:21], v[20:21], 0, s[6:7]
	v_lshl_add_u64 v[20:21], v[20:21], 0, v[136:137]
	v_add_f32_e32 v13, 1.0, v24
	v_add_f32_e32 v12, 1.0, v12
	global_store_dwordx4 v[20:21], v[16:19], off
	s_nop 1
	v_rcp_f32_e32 v16, v13
	v_rcp_f32_e32 v17, v12
	v_mov_b32_e32 v12, v10
	v_mov_b32_e32 v13, v14
	v_pk_mul_f32 v[12:13], v[12:13], v[118:119] op_sel_hi:[1,0]
	v_mul_f32_e32 v14, v23, v16
	v_mul_f32_e32 v10, 0xbfb8aa3b, v13
	v_exp_f32_e32 v10, v10
	v_mul_f32_e32 v16, v22, v14
	v_mov_b32_e32 v14, v11
	v_mul_f32_e32 v9, v9, v17
	v_add_f32_e32 v10, 1.0, v10
	v_rcp_f32_e32 v17, v10
	v_pk_mul_f32 v[10:11], v[14:15], v[118:119] op_sel_hi:[1,0]
	v_mul_f32_e32 v15, v8, v9
	v_mul_f32_e32 v14, 0xbfb8aa3b, v11
	v_exp_f32_e32 v14, v14
	v_mul_f32_e32 v8, v13, v17
	v_mul_f32_e32 v12, v12, v8
	v_mov_b32_e32 v9, v4
	v_add_f32_e32 v8, 1.0, v14
	v_rcp_f32_e32 v13, v8
	v_mov_b32_e32 v8, v0
	v_pk_mul_f32 v[8:9], v[8:9], v[118:119] op_sel_hi:[1,0]
	s_nop 0
	v_mul_f32_e32 v0, 0xbfb8aa3b, v9
	v_exp_f32_e32 v4, v0
	v_mul_f32_e32 v0, v11, v13
	v_mul_f32_e32 v10, v10, v0
	v_cvt_pk_bf16_f32 v0, v16, v15
	v_add_f32_e32 v4, 1.0, v4
	v_rcp_f32_e32 v11, v4
	v_mov_b32_e32 v4, v1
	v_pk_mul_f32 v[4:5], v[4:5], v[118:119] op_sel_hi:[1,0]
	v_mul_f32_e32 v9, v9, v11
	v_mul_f32_e32 v1, 0xbfb8aa3b, v5
	v_exp_f32_e32 v13, v1
	v_cvt_pk_bf16_f32 v1, v12, v10
	v_mul_f32_e32 v10, v8, v9
	v_mov_b32_e32 v9, v6
	v_add_f32_e32 v8, 1.0, v13
	v_rcp_f32_e32 v11, v8
	v_mov_b32_e32 v8, v2
	v_pk_mul_f32 v[8:9], v[8:9], v[118:119] op_sel_hi:[1,0]
	v_mov_b32_e32 v6, v3
	v_mul_f32_e32 v2, 0xbfb8aa3b, v9
	v_exp_f32_e32 v12, v2
	v_pk_mul_f32 v[2:3], v[6:7], v[118:119] op_sel_hi:[1,0]
	v_mul_f32_e32 v5, v5, v11
	v_mul_f32_e32 v6, 0xbfb8aa3b, v3
	v_exp_f32_e32 v6, v6
	v_add_f32_e32 v7, 1.0, v12
	v_rcp_f32_e32 v7, v7
	v_mul_f32_e32 v4, v4, v5
	v_add_f32_e32 v6, 1.0, v6
	v_rcp_f32_e32 v6, v6
	v_mul_f32_e32 v5, v9, v7
	v_mul_f32_e32 v5, v8, v5
	v_mul_f32_e32 v3, v3, v6
	v_mul_f32_e32 v3, v2, v3
	v_cvt_pk_bf16_f32 v2, v10, v4
	v_cvt_pk_bf16_f32 v3, v5, v3
	v_mad_i64_i32 v[4:5], s[12:13], v116, s70, v[112:113]
	v_lshl_add_u64 v[4:5], v[4:5], 0, s[28:29]
	v_lshl_add_u64 v[4:5], v[4:5], 0, s[6:7]
	v_lshl_add_u64 v[4:5], v[4:5], 0, v[136:137]
	global_store_dwordx4 v[4:5], v[0:3], off
	s_cbranch_vccnz .LBB0_843
	s_andn2_b64 vcc, exec, s[8:9]
	s_cbranch_vccnz .LBB0_842
	s_barrier
	s_branch .LBB0_842

.LBB0_1736:
	s_lshl_b32 s10, s10, 5
	s_and_b32 s18, s10, 0x60
	s_mov_b64 s[10:11], 0x80
	s_add_i32 m0, s42, 0x18000
	v_lshl_add_u64 v[6:7], v[6:7], 0, s[10:11]
	s_lshl_b32 s16, s6, 13
	s_lshl_b32 s17, s18, 7
	s_waitcnt vmcnt(2)
	s_barrier
	global_load_lds_dwordx4 v[6:7], off
	v_lshl_add_u64 v[4:5], v[4:5], 0, s[10:11]
	s_add_i32 m0, s42, 0x1a000
	s_add_i32 s46, s42, 0x8000
	s_add_i32 s47, s42, 0xa000
	global_load_lds_dwordx4 v[4:5], off
	v_lshl_add_u64 v[0:1], v[0:1], 0, s[10:11]
	s_mov_b32 m0, s46
	s_add_u32 s12, s30, 0x40080
	global_load_lds_dwordx4 v[0:1], off
	v_lshl_add_u64 v[0:1], v[2:3], 0, s[10:11]
	s_mov_b32 m0, s47
	s_addc_u32 s13, s31, 0
	global_load_lds_dwordx4 v[0:1], off
	s_add_i32 m0, s42, 0x1c000
	v_lshl_add_u64 v[0:1], s[12:13], 0, v[128:129]
	global_load_lds_dwordx4 v[0:1], off
	v_lshl_add_u64 v[0:1], s[12:13], 0, v[130:131]
	s_add_i32 m0, s42, 0x1e000
	s_cmpk_lt_u32 s5, 0x100
	global_load_lds_dwordx4 v[0:1], off
	v_lshrrev_b32_e32 v0, 1, v9
	v_and_b32_e32 v0, 24, v0
	v_and_b32_e32 v1, 15, v9
	v_lshlrev_b32_e32 v2, 1, v0
	v_lshl_or_b32 v157, s6, 6, v1
	v_lshl_or_b32 v1, v1, 6, v2
	v_lshlrev_b32_e32 v2, 2, v9
	v_and_b32_e32 v2, 32, v2
	v_bitop3_b32 v3, v1, s16, v2 bitop3:0xde
	v_bitop3_b32 v161, v1, s17, v2 bitop3:0xde
	v_lshlrev_b32_e32 v1, 14, v13
	v_and_b32_e32 v1, 0xffff8000, v1
	v_lshl_add_u32 v1, v12, 11, v1
	v_and_b32_e32 v2, 1, v13
	v_lshl_or_b32 v1, v2, 6, v1
	v_lshl_add_u32 v138, v14, 1, v1
	v_lshlrev_b32_e32 v1, 14, v8
	v_and_b32_e32 v1, 0xffff8000, v1
	s_waitcnt vmcnt(6)
	v_lshl_add_u32 v1, v10, 11, v1
	v_and_b32_e32 v2, 1, v8
	s_cselect_b64 s[16:17], -1, 0
	v_mov_b32_e32 v137, 0
	v_lshl_or_b32 v1, v2, 6, v1
	s_add_i32 s50, 0, 0x10000
	s_add_i32 s51, 0, 0x14000
	s_sext_i32_i16 s27, s4
	s_ashr_i32 s48, s58, 31
	s_mov_b32 s49, s58
	v_mov_b32_e32 v139, v137
	v_lshl_add_u32 v140, v11, 1, v1
	v_mov_b32_e32 v141, v137
	v_mov_b64_e32 v[142:143], 0x580
	v_mov_b64_e32 v[144:145], 0x57f
	v_add_u32_e32 v162, s50, v161
	v_add_u32_e32 v163, s51, v161
	v_add_u32_e32 v164, 0, v3
	s_movk_i32 s52, 0x1600
	s_lshl_b32 s6, s18, 1
	v_lshlrev_b32_e32 v136, 1, v0
	s_mov_b32 s53, s7
	s_barrier
	v_lshl_add_u32 v232, s26, 8, v157
	v_lshlrev_b32_e32 v232, 2, v232
	global_load_dword v233, v232, s[66:67]
	global_load_dword v234, v232, s[66:67] offset:64
	global_load_dword v235, v232, s[66:67] offset:128
	global_load_dword v236, v232, s[66:67] offset:192
	global_load_dword v237, v232, s[66:67] offset:512
	global_load_dword v238, v232, s[66:67] offset:576
	global_load_dword v239, v232, s[66:67] offset:640
	global_load_dword v240, v232, s[66:67] offset:704
	s_branch .LBB0_1739

.LBB0_1745:
	v_lshl_add_u32 v166, s26, 8, v157
	v_ashrrev_i32_e32 v167, 31, v166
	v_lshl_add_u64 v[146:147], v[166:167], 2, s[66:67]
	v_mov_b32_e32 v168, v233
	v_or_b32_e32 v178, 16, v166
	v_ashrrev_i32_e32 v179, 31, v178
	v_mov_b32_e32 v176, v118
	v_mov_b32_e32 v177, v114
	v_mov_b32_e32 v114, v119
	v_lshl_add_u64 v[118:119], v[178:179], 2, s[66:67]
	v_mov_b32_e32 v182, v234
	v_or_b32_e32 v158, 32, v166
	v_add_u32_e32 v150, 0x80, v166
	v_mov_b32_e32 v170, v124
	v_mov_b32_e32 v171, v120
	v_mov_b32_e32 v174, v116
	v_or_b32_e32 v154, 48, v166
	v_add_u32_e32 v146, 0x90, v166
	v_add_u32_e32 v124, 0xa0, v166
	v_add_u32_e32 v116, 0xb0, v166
	v_ashrrev_i32_e32 v159, 31, v158
	v_ashrrev_i32_e32 v151, 31, v150
	v_mov_b32_e32 v120, v125
	v_mov_b32_e32 v172, v126
	v_mov_b32_e32 v173, v122
	v_mov_b32_e32 v122, v127
	v_mov_b32_e32 v175, v112
	v_mov_b32_e32 v112, v117
	v_ashrrev_i32_e32 v155, 31, v154
	v_ashrrev_i32_e32 v147, 31, v146
	v_ashrrev_i32_e32 v125, 31, v124
	v_ashrrev_i32_e32 v117, 31, v116
	v_lshl_add_u64 v[126:127], v[158:159], 2, s[66:67]
	v_lshl_add_u64 v[118:119], v[150:151], 2, s[66:67]
	v_lshl_add_u64 v[180:181], v[154:155], 2, s[66:67]
	v_lshl_add_u64 v[184:185], v[146:147], 2, s[66:67]
	v_lshl_add_u64 v[186:187], v[124:125], 2, s[66:67]
	v_lshl_add_u64 v[188:189], v[116:117], 2, s[66:67]
	v_mov_b32_e32 v160, v235
	v_mov_b32_e32 v156, v236
	v_mov_b32_e32 v152, v237
	v_mov_b32_e32 v148, v238
	s_nop 0
	v_mov_b32_e32 v126, v239
	v_mov_b32_e32 v118, v240
	s_cmp_lg_u64 s[4:5], 0
	s_cselect_b32 s92, s20, s26
	v_lshl_add_u32 v232, s92, 8, v157
	v_lshlrev_b32_e32 v232, 2, v232
	global_load_dword v233, v232, s[66:67]
	global_load_dword v234, v232, s[66:67] offset:64
	global_load_dword v235, v232, s[66:67] offset:128
	global_load_dword v236, v232, s[66:67] offset:192
	global_load_dword v237, v232, s[66:67] offset:512
	global_load_dword v238, v232, s[66:67] offset:576
	global_load_dword v239, v232, s[66:67] offset:640
	global_load_dword v240, v232, s[66:67] offset:704
	v_mov_b32_e32 v167, v108
	v_mov_b32_e32 v108, v105
	s_lshl_b32 s26, s27, 7
	s_ashr_i32 s27, s26, 31
	s_lshl_b64 s[26:27], s[26:27], 1
	s_andn2_b64 vcc, exec, s[4:5]
	s_mov_b64 s[4:5], -1
	v_pk_mul_f32 v[170:171], v[170:171], v[168:169] op_sel_hi:[1,0]
	v_pk_mul_f32 v[120:121], v[120:121], v[168:169] op_sel_hi:[1,0]
	v_mul_f32_e32 v117, 0xbfb8aa3b, v171
	v_mul_f32_e32 v119, 0xbfb8aa3b, v121
	v_exp_f32_e32 v117, v117
	v_exp_f32_e32 v119, v119
	v_pk_mul_f32 v[112:113], v[112:113], v[168:169] op_sel_hi:[1,0]
	v_pk_mul_f32 v[172:173], v[172:173], v[168:169] op_sel_hi:[1,0]
	v_pk_mul_f32 v[122:123], v[122:123], v[168:169] op_sel_hi:[1,0]
	v_pk_mul_f32 v[174:175], v[174:175], v[168:169] op_sel_hi:[1,0]
	v_pk_mul_f32 v[176:177], v[176:177], v[168:169] op_sel_hi:[1,0]
	v_mul_f32_e32 v151, 0xbfb8aa3b, v113
	v_add_f32_e32 v117, 1.0, v117
	v_pk_mul_f32 v[114:115], v[114:115], v[168:169] op_sel_hi:[1,0]
	v_mul_f32_e32 v125, 0xbfb8aa3b, v173
	v_mul_f32_e32 v127, 0xbfb8aa3b, v123
	v_mul_f32_e32 v147, 0xbfb8aa3b, v175
	v_mul_f32_e32 v155, 0xbfb8aa3b, v177
	v_exp_f32_e32 v151, v151
	v_add_f32_e32 v119, 1.0, v119
	v_rcp_f32_e32 v117, v117
	v_mul_f32_e32 v159, 0xbfb8aa3b, v115
	v_exp_f32_e32 v125, v125
	v_exp_f32_e32 v127, v127
	v_exp_f32_e32 v147, v147
	v_exp_f32_e32 v155, v155
	v_rcp_f32_e32 v119, v119
	v_exp_f32_e32 v159, v159
	v_add_f32_e32 v151, 1.0, v151
	v_mul_f32_e32 v117, v171, v117
	v_add_f32_e32 v125, 1.0, v125
	v_add_f32_e32 v127, 1.0, v127
	v_add_f32_e32 v147, 1.0, v147
	v_add_f32_e32 v155, 1.0, v155
	v_rcp_f32_e32 v151, v151
	v_mul_f32_e32 v119, v121, v119
	v_mul_f32_e32 v117, v170, v117
	v_rcp_f32_e32 v125, v125
	v_rcp_f32_e32 v127, v127
	v_rcp_f32_e32 v147, v147
	v_rcp_f32_e32 v155, v155
	v_mul_f32_e32 v119, v120, v119
	v_cvt_pk_bf16_f32 v120, v117, v119
	v_add_f32_e32 v117, 1.0, v159
	v_rcp_f32_e32 v117, v117
	v_mul_f32_e32 v113, v113, v151
	v_mul_f32_e32 v121, v173, v125
	v_mul_f32_e32 v123, v123, v127
	v_mul_f32_e32 v125, v175, v147
	v_mul_f32_e32 v112, v112, v113
	v_mul_f32_e32 v113, v177, v155
	v_mul_f32_e32 v121, v172, v121
	v_mul_f32_e32 v122, v122, v123
	v_mul_f32_e32 v123, v174, v125
	v_mul_f32_e32 v113, v176, v113
	v_mul_f32_e32 v115, v115, v117
	v_cvt_pk_bf16_f32 v121, v121, v122
	v_mul_f32_e32 v114, v114, v115
	v_cvt_pk_bf16_f32 v122, v123, v112
	v_cvt_pk_bf16_f32 v123, v113, v114
	v_mov_b64_e32 v[112:113], s[64:65]
	v_mad_i64_i32 v[114:115], s[12:13], v166, s52, v[112:113]
	v_mov_b32_e32 v166, v104
	v_pk_mul_f32 v[166:167], v[166:167], v[182:183] op_sel_hi:[1,0]
	v_lshl_add_u64 v[114:115], v[114:115], 0, s[26:27]
	v_mul_f32_e32 v104, 0xbfb8aa3b, v167
	v_exp_f32_e32 v117, v104
	v_pk_mul_f32 v[104:105], v[108:109], v[182:183] op_sel_hi:[1,0]
	v_lshl_add_u64 v[114:115], v[114:115], 0, s[6:7]
	v_mul_f32_e32 v108, 0xbfb8aa3b, v105
	v_exp_f32_e32 v108, v108
	v_lshl_add_u64 v[114:115], v[114:115], 0, v[136:137]
	v_add_f32_e32 v109, 1.0, v117
	global_store_dwordx4 v[114:115], v[120:123], off
	v_add_f32_e32 v108, 1.0, v108
	v_rcp_f32_e32 v114, v109
	v_rcp_f32_e32 v115, v108
	v_mov_b32_e32 v108, v106
	v_mov_b32_e32 v109, v110
	v_pk_mul_f32 v[108:109], v[108:109], v[182:183] op_sel_hi:[1,0]
	v_mul_f32_e32 v110, v167, v114
	v_mul_f32_e32 v106, 0xbfb8aa3b, v109
	v_exp_f32_e32 v106, v106
	v_mul_f32_e32 v114, v166, v110
	v_mov_b32_e32 v110, v107
	v_mul_f32_e32 v105, v105, v115
	v_add_f32_e32 v106, 1.0, v106
	v_rcp_f32_e32 v115, v106
	v_pk_mul_f32 v[106:107], v[110:111], v[182:183] op_sel_hi:[1,0]
	v_mul_f32_e32 v111, v104, v105
	v_mul_f32_e32 v110, 0xbfb8aa3b, v107
	v_exp_f32_e32 v110, v110
	v_mul_f32_e32 v104, v109, v115
	v_mul_f32_e32 v108, v108, v104
	v_mov_b32_e32 v105, v100
	v_add_f32_e32 v104, 1.0, v110
	v_rcp_f32_e32 v109, v104
	v_mov_b32_e32 v104, v96
	v_pk_mul_f32 v[104:105], v[104:105], v[182:183] op_sel_hi:[1,0]
	s_nop 0
	v_mul_f32_e32 v96, 0xbfb8aa3b, v105
	v_exp_f32_e32 v100, v96
	v_mul_f32_e32 v96, v107, v109
	v_mul_f32_e32 v106, v106, v96
	v_cvt_pk_bf16_f32 v96, v114, v111
	v_add_f32_e32 v100, 1.0, v100
	v_rcp_f32_e32 v107, v100
	v_mov_b32_e32 v100, v97
	v_pk_mul_f32 v[100:101], v[100:101], v[182:183] op_sel_hi:[1,0]
	v_mul_f32_e32 v105, v105, v107
	v_mul_f32_e32 v97, 0xbfb8aa3b, v101
	v_exp_f32_e32 v109, v97
	v_cvt_pk_bf16_f32 v97, v108, v106
	v_mul_f32_e32 v106, v104, v105
	v_mov_b32_e32 v105, v102
	v_add_f32_e32 v104, 1.0, v109
	v_rcp_f32_e32 v107, v104
	v_mov_b32_e32 v104, v98
	v_pk_mul_f32 v[104:105], v[104:105], v[182:183] op_sel_hi:[1,0]
	v_mov_b32_e32 v102, v99
	v_mul_f32_e32 v98, 0xbfb8aa3b, v105
	v_exp_f32_e32 v108, v98
	v_pk_mul_f32 v[98:99], v[102:103], v[182:183] op_sel_hi:[1,0]
	v_mul_f32_e32 v101, v101, v107
	v_mul_f32_e32 v102, 0xbfb8aa3b, v99
	v_exp_f32_e32 v102, v102
	v_add_f32_e32 v103, 1.0, v108
	v_rcp_f32_e32 v103, v103
	v_mul_f32_e32 v100, v100, v101
	v_add_f32_e32 v102, 1.0, v102
	v_rcp_f32_e32 v102, v102
	v_mul_f32_e32 v101, v105, v103
	v_mov_b32_e32 v103, v92
	v_mov_b32_e32 v92, v89
	v_mul_f32_e32 v99, v99, v102
	v_mov_b32_e32 v102, v88
	v_pk_mul_f32 v[102:103], v[102:103], v[160:161] op_sel_hi:[1,0]
	v_mul_f32_e32 v101, v104, v101
	v_mul_f32_e32 v88, 0xbfb8aa3b, v103
	v_exp_f32_e32 v104, v88
	v_pk_mul_f32 v[88:89], v[92:93], v[160:161] op_sel_hi:[1,0]
	v_mul_f32_e32 v99, v98, v99
	v_mul_f32_e32 v92, 0xbfb8aa3b, v89
	v_exp_f32_e32 v92, v92
	v_cvt_pk_bf16_f32 v98, v106, v100
	v_cvt_pk_bf16_f32 v99, v101, v99
	v_mad_i64_i32 v[100:101], s[12:13], v178, s52, v[112:113]
	v_lshl_add_u64 v[100:101], v[100:101], 0, s[26:27]
	v_lshl_add_u64 v[100:101], v[100:101], 0, s[6:7]
	v_lshl_add_u64 v[100:101], v[100:101], 0, v[136:137]
	v_add_f32_e32 v93, 1.0, v104
	v_add_f32_e32 v92, 1.0, v92
	global_store_dwordx4 v[100:101], v[96:99], off
	s_nop 1
	v_rcp_f32_e32 v96, v93
	v_rcp_f32_e32 v97, v92
	v_mov_b32_e32 v92, v90
	v_mov_b32_e32 v93, v94
	v_pk_mul_f32 v[92:93], v[92:93], v[160:161] op_sel_hi:[1,0]
	v_mul_f32_e32 v94, v103, v96
	v_mul_f32_e32 v90, 0xbfb8aa3b, v93
	v_exp_f32_e32 v90, v90
	v_mul_f32_e32 v96, v102, v94
	v_mov_b32_e32 v94, v91
	v_mul_f32_e32 v89, v89, v97
	v_add_f32_e32 v90, 1.0, v90
	v_rcp_f32_e32 v97, v90
	v_pk_mul_f32 v[90:91], v[94:95], v[160:161] op_sel_hi:[1,0]
	v_mul_f32_e32 v95, v88, v89
	v_mul_f32_e32 v94, 0xbfb8aa3b, v91
	v_exp_f32_e32 v94, v94
	v_mul_f32_e32 v88, v93, v97
	v_mul_f32_e32 v92, v92, v88
	v_mov_b32_e32 v89, v84
	v_add_f32_e32 v88, 1.0, v94
	v_rcp_f32_e32 v93, v88
	v_mov_b32_e32 v88, v80
	v_pk_mul_f32 v[88:89], v[88:89], v[160:161] op_sel_hi:[1,0]
	s_nop 0
	v_mul_f32_e32 v80, 0xbfb8aa3b, v89
	v_exp_f32_e32 v84, v80
	v_mul_f32_e32 v80, v91, v93
	v_mul_f32_e32 v90, v90, v80
	v_cvt_pk_bf16_f32 v80, v96, v95
	v_add_f32_e32 v84, 1.0, v84
	v_rcp_f32_e32 v91, v84
	v_mov_b32_e32 v84, v81
	v_pk_mul_f32 v[84:85], v[84:85], v[160:161] op_sel_hi:[1,0]
	v_mul_f32_e32 v89, v89, v91
	v_mul_f32_e32 v81, 0xbfb8aa3b, v85
	v_exp_f32_e32 v93, v81
	v_cvt_pk_bf16_f32 v81, v92, v90
	v_mul_f32_e32 v90, v88, v89
	v_mov_b32_e32 v89, v86
	v_add_f32_e32 v88, 1.0, v93
	v_rcp_f32_e32 v91, v88
	v_mov_b32_e32 v88, v82
	v_pk_mul_f32 v[88:89], v[88:89], v[160:161] op_sel_hi:[1,0]
	v_mov_b32_e32 v86, v83
	v_mul_f32_e32 v82, 0xbfb8aa3b, v89
	v_exp_f32_e32 v92, v82
	v_pk_mul_f32 v[82:83], v[86:87], v[160:161] op_sel_hi:[1,0]
	v_mul_f32_e32 v85, v85, v91
	v_mul_f32_e32 v86, 0xbfb8aa3b, v83
	v_exp_f32_e32 v86, v86
	v_add_f32_e32 v87, 1.0, v92
	v_rcp_f32_e32 v87, v87
	v_mul_f32_e32 v84, v84, v85
	v_add_f32_e32 v86, 1.0, v86
	v_rcp_f32_e32 v86, v86
	v_mul_f32_e32 v85, v89, v87
	v_mov_b32_e32 v87, v76
	v_mov_b32_e32 v76, v73
	v_mul_f32_e32 v83, v83, v86
	v_mov_b32_e32 v86, v72
	v_pk_mul_f32 v[86:87], v[86:87], v[156:157] op_sel_hi:[1,0]
	v_mul_f32_e32 v85, v88, v85
	v_mul_f32_e32 v72, 0xbfb8aa3b, v87
	v_exp_f32_e32 v88, v72
	v_pk_mul_f32 v[72:73], v[76:77], v[156:157] op_sel_hi:[1,0]
	v_mul_f32_e32 v83, v82, v83
	v_mul_f32_e32 v76, 0xbfb8aa3b, v73
	v_exp_f32_e32 v76, v76
	v_cvt_pk_bf16_f32 v82, v90, v84
	v_cvt_pk_bf16_f32 v83, v85, v83
	v_mad_i64_i32 v[84:85], s[12:13], v158, s52, v[112:113]
	v_lshl_add_u64 v[84:85], v[84:85], 0, s[26:27]
	v_lshl_add_u64 v[84:85], v[84:85], 0, s[6:7]
	v_lshl_add_u64 v[84:85], v[84:85], 0, v[136:137]
	v_add_f32_e32 v77, 1.0, v88
	v_add_f32_e32 v76, 1.0, v76
	global_store_dwordx4 v[84:85], v[80:83], off
	s_nop 1
	v_rcp_f32_e32 v80, v77
	v_rcp_f32_e32 v81, v76
	v_mov_b32_e32 v76, v74
	v_mov_b32_e32 v77, v78
	v_pk_mul_f32 v[76:77], v[76:77], v[156:157] op_sel_hi:[1,0]
	v_mul_f32_e32 v78, v87, v80
	v_mul_f32_e32 v74, 0xbfb8aa3b, v77
	v_exp_f32_e32 v74, v74
	v_mul_f32_e32 v80, v86, v78
	v_mov_b32_e32 v78, v75
	v_mul_f32_e32 v73, v73, v81
	v_add_f32_e32 v74, 1.0, v74
	v_rcp_f32_e32 v81, v74
	v_pk_mul_f32 v[74:75], v[78:79], v[156:157] op_sel_hi:[1,0]
	v_mul_f32_e32 v79, v72, v73
	v_mul_f32_e32 v78, 0xbfb8aa3b, v75
	v_exp_f32_e32 v78, v78
	v_mul_f32_e32 v72, v77, v81
	v_mul_f32_e32 v76, v76, v72
	v_mov_b32_e32 v73, v68
	v_add_f32_e32 v72, 1.0, v78
	v_rcp_f32_e32 v77, v72
	v_mov_b32_e32 v72, v64
	v_pk_mul_f32 v[72:73], v[72:73], v[156:157] op_sel_hi:[1,0]
	s_nop 0
	v_mul_f32_e32 v64, 0xbfb8aa3b, v73
	v_exp_f32_e32 v68, v64
	v_mul_f32_e32 v64, v75, v77
	v_mul_f32_e32 v74, v74, v64
	v_cvt_pk_bf16_f32 v64, v80, v79
	v_add_f32_e32 v68, 1.0, v68
	v_rcp_f32_e32 v75, v68
	v_mov_b32_e32 v68, v65
	v_pk_mul_f32 v[68:69], v[68:69], v[156:157] op_sel_hi:[1,0]
	v_mul_f32_e32 v73, v73, v75
	v_mul_f32_e32 v65, 0xbfb8aa3b, v69
	v_exp_f32_e32 v77, v65
	v_cvt_pk_bf16_f32 v65, v76, v74
	v_mul_f32_e32 v74, v72, v73
	v_mov_b32_e32 v73, v70
	v_add_f32_e32 v72, 1.0, v77
	v_rcp_f32_e32 v75, v72
	v_mov_b32_e32 v72, v66
	v_pk_mul_f32 v[72:73], v[72:73], v[156:157] op_sel_hi:[1,0]
	v_mov_b32_e32 v70, v67
	v_mul_f32_e32 v66, 0xbfb8aa3b, v73
	v_exp_f32_e32 v76, v66
	v_pk_mul_f32 v[66:67], v[70:71], v[156:157] op_sel_hi:[1,0]
	v_mul_f32_e32 v69, v69, v75
	v_mul_f32_e32 v70, 0xbfb8aa3b, v67
	v_exp_f32_e32 v70, v70
	v_add_f32_e32 v71, 1.0, v76
	v_rcp_f32_e32 v71, v71
	v_mul_f32_e32 v68, v68, v69
	v_add_f32_e32 v70, 1.0, v70
	v_rcp_f32_e32 v70, v70
	v_mul_f32_e32 v69, v73, v71
	v_mov_b32_e32 v71, v60
	v_mov_b32_e32 v60, v57
	v_mul_f32_e32 v67, v67, v70
	v_mov_b32_e32 v70, v56
	v_pk_mul_f32 v[70:71], v[70:71], v[152:153] op_sel_hi:[1,0]
	v_mul_f32_e32 v69, v72, v69
	v_mul_f32_e32 v56, 0xbfb8aa3b, v71
	v_exp_f32_e32 v72, v56
	v_pk_mul_f32 v[56:57], v[60:61], v[152:153] op_sel_hi:[1,0]
	v_mul_f32_e32 v67, v66, v67
	v_mul_f32_e32 v60, 0xbfb8aa3b, v57
	v_exp_f32_e32 v60, v60
	v_cvt_pk_bf16_f32 v66, v74, v68
	v_cvt_pk_bf16_f32 v67, v69, v67
	v_mad_i64_i32 v[68:69], s[12:13], v154, s52, v[112:113]
	v_lshl_add_u64 v[68:69], v[68:69], 0, s[26:27]
	v_lshl_add_u64 v[68:69], v[68:69], 0, s[6:7]
	v_lshl_add_u64 v[68:69], v[68:69], 0, v[136:137]
	v_add_f32_e32 v61, 1.0, v72
	v_add_f32_e32 v60, 1.0, v60
	global_store_dwordx4 v[68:69], v[64:67], off
	s_nop 1
	v_rcp_f32_e32 v64, v61
	v_rcp_f32_e32 v65, v60
	v_mov_b32_e32 v60, v58
	v_mov_b32_e32 v61, v62
	v_pk_mul_f32 v[60:61], v[60:61], v[152:153] op_sel_hi:[1,0]
	v_mul_f32_e32 v62, v71, v64
	v_mul_f32_e32 v58, 0xbfb8aa3b, v61
	v_exp_f32_e32 v58, v58
	v_mul_f32_e32 v64, v70, v62
	v_mov_b32_e32 v62, v59
	v_mul_f32_e32 v57, v57, v65
	v_add_f32_e32 v58, 1.0, v58
	v_rcp_f32_e32 v65, v58
	v_pk_mul_f32 v[58:59], v[62:63], v[152:153] op_sel_hi:[1,0]
	v_mul_f32_e32 v63, v56, v57
	v_mul_f32_e32 v62, 0xbfb8aa3b, v59
	v_exp_f32_e32 v62, v62
	v_mul_f32_e32 v56, v61, v65
	v_mul_f32_e32 v60, v60, v56
	v_mov_b32_e32 v57, v52
	v_add_f32_e32 v56, 1.0, v62
	v_rcp_f32_e32 v61, v56
	v_mov_b32_e32 v56, v48
	v_pk_mul_f32 v[56:57], v[56:57], v[152:153] op_sel_hi:[1,0]
	s_nop 0
	v_mul_f32_e32 v48, 0xbfb8aa3b, v57
	v_exp_f32_e32 v52, v48
	v_mul_f32_e32 v48, v59, v61
	v_mul_f32_e32 v58, v58, v48
	v_cvt_pk_bf16_f32 v48, v64, v63
	v_add_f32_e32 v52, 1.0, v52
	v_rcp_f32_e32 v59, v52
	v_mov_b32_e32 v52, v49
	v_pk_mul_f32 v[52:53], v[52:53], v[152:153] op_sel_hi:[1,0]
	v_mul_f32_e32 v57, v57, v59
	v_mul_f32_e32 v49, 0xbfb8aa3b, v53
	v_exp_f32_e32 v61, v49
	v_cvt_pk_bf16_f32 v49, v60, v58
	v_mul_f32_e32 v58, v56, v57
	v_mov_b32_e32 v57, v54
	v_add_f32_e32 v56, 1.0, v61
	v_rcp_f32_e32 v59, v56
	v_mov_b32_e32 v56, v50
	v_pk_mul_f32 v[56:57], v[56:57], v[152:153] op_sel_hi:[1,0]
	v_mov_b32_e32 v54, v51
	v_mul_f32_e32 v50, 0xbfb8aa3b, v57
	v_exp_f32_e32 v60, v50
	v_pk_mul_f32 v[50:51], v[54:55], v[152:153] op_sel_hi:[1,0]
	v_mul_f32_e32 v53, v53, v59
	v_mul_f32_e32 v54, 0xbfb8aa3b, v51
	v_exp_f32_e32 v54, v54
	v_add_f32_e32 v55, 1.0, v60
	v_rcp_f32_e32 v55, v55
	v_mul_f32_e32 v52, v52, v53
	v_add_f32_e32 v54, 1.0, v54
	v_rcp_f32_e32 v54, v54
	v_mul_f32_e32 v53, v57, v55
	v_mov_b32_e32 v55, v44
	v_mov_b32_e32 v44, v41
	v_mul_f32_e32 v51, v51, v54
	v_mov_b32_e32 v54, v40
	v_pk_mul_f32 v[54:55], v[54:55], v[148:149] op_sel_hi:[1,0]
	v_mul_f32_e32 v53, v56, v53
	v_mul_f32_e32 v40, 0xbfb8aa3b, v55
	v_exp_f32_e32 v56, v40
	v_pk_mul_f32 v[40:41], v[44:45], v[148:149] op_sel_hi:[1,0]
	v_mul_f32_e32 v51, v50, v51
	v_mul_f32_e32 v44, 0xbfb8aa3b, v41
	v_exp_f32_e32 v44, v44
	v_cvt_pk_bf16_f32 v50, v58, v52
	v_cvt_pk_bf16_f32 v51, v53, v51
	v_mad_i64_i32 v[52:53], s[12:13], v150, s52, v[112:113]
	v_lshl_add_u64 v[52:53], v[52:53], 0, s[26:27]
	v_lshl_add_u64 v[52:53], v[52:53], 0, s[6:7]
	v_lshl_add_u64 v[52:53], v[52:53], 0, v[136:137]
	v_add_f32_e32 v45, 1.0, v56
	v_add_f32_e32 v44, 1.0, v44
	global_store_dwordx4 v[52:53], v[48:51], off
	s_nop 1
	v_rcp_f32_e32 v48, v45
	v_rcp_f32_e32 v49, v44
	v_mov_b32_e32 v44, v42
	v_mov_b32_e32 v45, v46
	v_pk_mul_f32 v[44:45], v[44:45], v[148:149] op_sel_hi:[1,0]
	v_mul_f32_e32 v46, v55, v48
	v_mul_f32_e32 v42, 0xbfb8aa3b, v45
	v_exp_f32_e32 v42, v42
	v_mul_f32_e32 v48, v54, v46
	v_mov_b32_e32 v46, v43
	v_mul_f32_e32 v41, v41, v49
	v_add_f32_e32 v42, 1.0, v42
	v_rcp_f32_e32 v49, v42
	v_pk_mul_f32 v[42:43], v[46:47], v[148:149] op_sel_hi:[1,0]
	v_mul_f32_e32 v47, v40, v41
	v_mul_f32_e32 v46, 0xbfb8aa3b, v43
	v_exp_f32_e32 v46, v46
	v_mul_f32_e32 v40, v45, v49
	v_mul_f32_e32 v44, v44, v40
	v_mov_b32_e32 v41, v36
	v_add_f32_e32 v40, 1.0, v46
	v_rcp_f32_e32 v45, v40
	v_mov_b32_e32 v40, v32
	v_pk_mul_f32 v[40:41], v[40:41], v[148:149] op_sel_hi:[1,0]
	s_nop 0
	v_mul_f32_e32 v32, 0xbfb8aa3b, v41
	v_exp_f32_e32 v36, v32
	v_mul_f32_e32 v32, v43, v45
	v_mul_f32_e32 v42, v42, v32
	v_cvt_pk_bf16_f32 v32, v48, v47
	v_add_f32_e32 v36, 1.0, v36
	v_rcp_f32_e32 v43, v36
	v_mov_b32_e32 v36, v33
	v_pk_mul_f32 v[36:37], v[36:37], v[148:149] op_sel_hi:[1,0]
	v_mul_f32_e32 v41, v41, v43
	v_mul_f32_e32 v33, 0xbfb8aa3b, v37
	v_exp_f32_e32 v45, v33
	v_cvt_pk_bf16_f32 v33, v44, v42
	v_mul_f32_e32 v42, v40, v41
	v_mov_b32_e32 v41, v38
	v_add_f32_e32 v40, 1.0, v45
	v_rcp_f32_e32 v43, v40
	v_mov_b32_e32 v40, v34
	v_pk_mul_f32 v[40:41], v[40:41], v[148:149] op_sel_hi:[1,0]
	v_mov_b32_e32 v38, v35
	v_mul_f32_e32 v34, 0xbfb8aa3b, v41
	v_exp_f32_e32 v44, v34
	v_pk_mul_f32 v[34:35], v[38:39], v[148:149] op_sel_hi:[1,0]
	v_mul_f32_e32 v37, v37, v43
	v_mul_f32_e32 v38, 0xbfb8aa3b, v35
	v_exp_f32_e32 v38, v38
	v_add_f32_e32 v39, 1.0, v44
	v_rcp_f32_e32 v39, v39
	v_mul_f32_e32 v36, v36, v37
	v_add_f32_e32 v38, 1.0, v38
	v_rcp_f32_e32 v38, v38
	v_mul_f32_e32 v37, v41, v39
	v_mov_b32_e32 v39, v28
	v_mov_b32_e32 v28, v25
	v_mul_f32_e32 v35, v35, v38
	v_mov_b32_e32 v38, v24
	v_pk_mul_f32 v[38:39], v[38:39], v[126:127] op_sel_hi:[1,0]
	v_mul_f32_e32 v37, v40, v37
	v_mul_f32_e32 v24, 0xbfb8aa3b, v39
	v_exp_f32_e32 v40, v24
	v_pk_mul_f32 v[24:25], v[28:29], v[126:127] op_sel_hi:[1,0]
	v_mul_f32_e32 v35, v34, v35
	v_mul_f32_e32 v28, 0xbfb8aa3b, v25
	v_exp_f32_e32 v28, v28
	v_cvt_pk_bf16_f32 v34, v42, v36
	v_cvt_pk_bf16_f32 v35, v37, v35
	v_mad_i64_i32 v[36:37], s[12:13], v146, s52, v[112:113]
	v_lshl_add_u64 v[36:37], v[36:37], 0, s[26:27]
	v_lshl_add_u64 v[36:37], v[36:37], 0, s[6:7]
	v_lshl_add_u64 v[36:37], v[36:37], 0, v[136:137]
	v_add_f32_e32 v29, 1.0, v40
	v_add_f32_e32 v28, 1.0, v28
	global_store_dwordx4 v[36:37], v[32:35], off
	s_nop 1
	v_rcp_f32_e32 v32, v29
	v_rcp_f32_e32 v33, v28
	v_mov_b32_e32 v28, v26
	v_mov_b32_e32 v29, v30
	v_pk_mul_f32 v[28:29], v[28:29], v[126:127] op_sel_hi:[1,0]
	v_mul_f32_e32 v30, v39, v32
	v_mul_f32_e32 v26, 0xbfb8aa3b, v29
	v_exp_f32_e32 v26, v26
	v_mul_f32_e32 v32, v38, v30
	v_mov_b32_e32 v30, v27
	v_mul_f32_e32 v25, v25, v33
	v_add_f32_e32 v26, 1.0, v26
	v_rcp_f32_e32 v33, v26
	v_pk_mul_f32 v[26:27], v[30:31], v[126:127] op_sel_hi:[1,0]
	v_mul_f32_e32 v31, v24, v25
	v_mul_f32_e32 v30, 0xbfb8aa3b, v27
	v_exp_f32_e32 v30, v30
	v_mul_f32_e32 v24, v29, v33
	v_mul_f32_e32 v28, v28, v24
	v_mov_b32_e32 v25, v20
	v_add_f32_e32 v24, 1.0, v30
	v_rcp_f32_e32 v29, v24
	v_mov_b32_e32 v24, v16
	v_pk_mul_f32 v[24:25], v[24:25], v[126:127] op_sel_hi:[1,0]
	s_nop 0
	v_mul_f32_e32 v16, 0xbfb8aa3b, v25
	v_exp_f32_e32 v20, v16
	v_mul_f32_e32 v16, v27, v29
	v_mul_f32_e32 v26, v26, v16
	v_cvt_pk_bf16_f32 v16, v32, v31
	v_add_f32_e32 v20, 1.0, v20
	v_rcp_f32_e32 v27, v20
	v_mov_b32_e32 v20, v17
	v_pk_mul_f32 v[20:21], v[20:21], v[126:127] op_sel_hi:[1,0]
	v_mul_f32_e32 v25, v25, v27
	v_mul_f32_e32 v17, 0xbfb8aa3b, v21
	v_exp_f32_e32 v29, v17
	v_cvt_pk_bf16_f32 v17, v28, v26
	v_mul_f32_e32 v26, v24, v25
	v_mov_b32_e32 v25, v22
	v_add_f32_e32 v24, 1.0, v29
	v_rcp_f32_e32 v27, v24
	v_mov_b32_e32 v24, v18
	v_pk_mul_f32 v[24:25], v[24:25], v[126:127] op_sel_hi:[1,0]
	v_mov_b32_e32 v22, v19
	v_mul_f32_e32 v18, 0xbfb8aa3b, v25
	v_exp_f32_e32 v28, v18
	v_pk_mul_f32 v[18:19], v[22:23], v[126:127] op_sel_hi:[1,0]
	v_mul_f32_e32 v21, v21, v27
	v_mul_f32_e32 v22, 0xbfb8aa3b, v19
	v_exp_f32_e32 v22, v22
	v_add_f32_e32 v23, 1.0, v28
	v_rcp_f32_e32 v23, v23
	v_mul_f32_e32 v20, v20, v21
	v_add_f32_e32 v22, 1.0, v22
	v_rcp_f32_e32 v22, v22
	v_mul_f32_e32 v21, v25, v23
	v_mov_b32_e32 v23, v12
	v_mov_b32_e32 v12, v9
	v_mul_f32_e32 v19, v19, v22
	v_mov_b32_e32 v22, v8
	v_pk_mul_f32 v[22:23], v[22:23], v[118:119] op_sel_hi:[1,0]
	v_mul_f32_e32 v21, v24, v21
	v_mul_f32_e32 v8, 0xbfb8aa3b, v23
	v_exp_f32_e32 v24, v8
	v_pk_mul_f32 v[8:9], v[12:13], v[118:119] op_sel_hi:[1,0]
	v_mul_f32_e32 v19, v18, v19
	v_mul_f32_e32 v12, 0xbfb8aa3b, v9
	v_exp_f32_e32 v12, v12
	v_cvt_pk_bf16_f32 v18, v26, v20
	v_cvt_pk_bf16_f32 v19, v21, v19
	v_mad_i64_i32 v[20:21], s[12:13], v124, s52, v[112:113]
	v_lshl_add_u64 v[20:21], v[20:21], 0, s[26:27]
	v_lshl_add_u64 v[20:21], v[20:21], 0, s[6:7]
	v_lshl_add_u64 v[20:21], v[20:21], 0, v[136:137]
	v_add_f32_e32 v13, 1.0, v24
	v_add_f32_e32 v12, 1.0, v12
	global_store_dwordx4 v[20:21], v[16:19], off
	s_nop 1
	v_rcp_f32_e32 v16, v13
	v_rcp_f32_e32 v17, v12
	v_mov_b32_e32 v12, v10
	v_mov_b32_e32 v13, v14
	v_pk_mul_f32 v[12:13], v[12:13], v[118:119] op_sel_hi:[1,0]
	v_mul_f32_e32 v14, v23, v16
	v_mul_f32_e32 v10, 0xbfb8aa3b, v13
	v_exp_f32_e32 v10, v10
	v_mul_f32_e32 v16, v22, v14
	v_mov_b32_e32 v14, v11
	v_mul_f32_e32 v9, v9, v17
	v_add_f32_e32 v10, 1.0, v10
	v_rcp_f32_e32 v17, v10
	v_pk_mul_f32 v[10:11], v[14:15], v[118:119] op_sel_hi:[1,0]
	v_mul_f32_e32 v15, v8, v9
	v_mul_f32_e32 v14, 0xbfb8aa3b, v11
	v_exp_f32_e32 v14, v14
	v_mul_f32_e32 v8, v13, v17
	v_mul_f32_e32 v12, v12, v8
	v_mov_b32_e32 v9, v4
	v_add_f32_e32 v8, 1.0, v14
	v_rcp_f32_e32 v13, v8
	v_mov_b32_e32 v8, v0
	v_pk_mul_f32 v[8:9], v[8:9], v[118:119] op_sel_hi:[1,0]
	s_nop 0
	v_mul_f32_e32 v0, 0xbfb8aa3b, v9
	v_exp_f32_e32 v4, v0
	v_mul_f32_e32 v0, v11, v13
	v_mul_f32_e32 v10, v10, v0
	v_cvt_pk_bf16_f32 v0, v16, v15
	v_add_f32_e32 v4, 1.0, v4
	v_rcp_f32_e32 v11, v4
	v_mov_b32_e32 v4, v1
	v_pk_mul_f32 v[4:5], v[4:5], v[118:119] op_sel_hi:[1,0]
	v_mul_f32_e32 v9, v9, v11
	v_mul_f32_e32 v1, 0xbfb8aa3b, v5
	v_exp_f32_e32 v13, v1
	v_cvt_pk_bf16_f32 v1, v12, v10
	v_mul_f32_e32 v10, v8, v9
	v_mov_b32_e32 v9, v6
	v_add_f32_e32 v8, 1.0, v13
	v_rcp_f32_e32 v11, v8
	v_mov_b32_e32 v8, v2
	v_pk_mul_f32 v[8:9], v[8:9], v[118:119] op_sel_hi:[1,0]
	v_mov_b32_e32 v6, v3
	v_mul_f32_e32 v2, 0xbfb8aa3b, v9
	v_exp_f32_e32 v12, v2
	v_pk_mul_f32 v[2:3], v[6:7], v[118:119] op_sel_hi:[1,0]
	v_mul_f32_e32 v5, v5, v11
	v_mul_f32_e32 v6, 0xbfb8aa3b, v3
	v_exp_f32_e32 v6, v6
	v_add_f32_e32 v7, 1.0, v12
	v_rcp_f32_e32 v7, v7
	v_mul_f32_e32 v4, v4, v5
	v_add_f32_e32 v6, 1.0, v6
	v_rcp_f32_e32 v6, v6
	v_mul_f32_e32 v5, v9, v7
	v_mul_f32_e32 v5, v8, v5
	v_mul_f32_e32 v3, v3, v6
	v_mul_f32_e32 v3, v2, v3
	v_cvt_pk_bf16_f32 v2, v10, v4
	v_cvt_pk_bf16_f32 v3, v5, v3
	v_mad_i64_i32 v[4:5], s[12:13], v116, s52, v[112:113]
	v_lshl_add_u64 v[4:5], v[4:5], 0, s[26:27]
	v_lshl_add_u64 v[4:5], v[4:5], 0, s[6:7]
	v_lshl_add_u64 v[4:5], v[4:5], 0, v[136:137]
	global_store_dwordx4 v[4:5], v[0:3], off
	s_cbranch_vccnz .LBB0_1738
	s_andn2_b64 vcc, exec, s[8:9]
	s_cbranch_vccnz .LBB0_1737
	s_barrier
	s_branch .LBB0_1737
